# attention loop: K-fragment LDS reads issued before K global loads, pointer increments moved into PV MFMA shadow; plus hand-written scan loop
# speedup vs baseline: 1.0493x; 1.0112x over previous
; __device__ __forceinline__ void attn_diff32(const bf16_t* __restrict__ Qp, const bf16_t* __restrict__ Kp,
;                                             const bf16_t* __restrict__ Vtp, int ntiles, float negM,
;                                             f32x4 (&o)[2][8], float (&l)[2], char* smem) {
;     ...
;   for (int n = 0; n < ntiles; ++n) {
;     __syncthreads();
;     *(uint4*)(sK + (lr) * LSTR + lch) = rk00;
;     *(uint4*)(sK + (lr + 32) * LSTR + lch) = rk01;
;     *(uint4*)(sK + (64 + lr) * LSTR + lch) = rk10;
;     *(uint4*)(sK + (64 + lr + 32) * LSTR + lch) = rk11;
;     *(uint4*)(sVt + (lr) * LSTR + lch) = rv0;
;     *(uint4*)(sVt + (lr + 32) * LSTR + lch) = rv1;
;     *(uint4*)(sVt + (lr + 64) * LSTR + lch) = rv2;
;     *(uint4*)(sVt + (lr + 96) * LSTR + lch) = rv3;
;     __syncthreads();
;     const int knext = (n + 1) * 64;
;     if (n + 1 < ntiles) { AD_LOAD_K(knext) }
;     f32x4 s[2][4];
;     __builtin_amdgcn_s_setprio(1);
; #pragma unroll
;     for (int kt = 0; kt < 4; ++kt) {
;       s[0][kt] = (f32x4){negM, negM, negM, negM};
;       s[1][kt] = (f32x4){negM, negM, negM, negM};
;       const int krow = 32 * (kt >> 1) + (l15 >> 2) * 8 + (kt & 1) * 4 + (l15 & 3);
; #pragma unroll
;       for (int ks = 0; ks < 2; ++ks) {
;         const bf16x8 kf = *(const bf16x8*)(sKc + krow * LSTR + ks * 32 + quad * 8);
;         s[0][kt] = __builtin_amdgcn_mfma_f32_16x16x32_bf16(kf, qf[0][ks], s[0][kt], 0, 0, 0);
;         s[1][kt] = __builtin_amdgcn_mfma_f32_16x16x32_bf16(kf, qf[1][ks], s[1][kt], 0, 0, 0);
;       }
;     }
;     __builtin_amdgcn_s_setprio(0);
;     bf16x8 pf[2][2];
; #pragma unroll
;     for (int qt = 0; qt < 2; ++qt) {
;       float ls = 0.f;
; #pragma unroll
;       for (int kt = 0; kt < 4; ++kt)
; #pragma unroll
;         for (int e = 0; e < 4; ++e) {
;           s[qt][kt][e] = fexp2(s[qt][kt][e]);
;           ls += s[qt][kt][e];
;         }
;       l[qt] += ls;
; #pragma unroll
;       for (int ks2 = 0; ks2 < 2; ++ks2) {
;         union { uint32_t u[4]; bf16x8 v; } pk;
;         pk.u[0] = pack2(s[qt][2 * ks2][0], s[qt][2 * ks2][1]);
;         pk.u[1] = pack2(s[qt][2 * ks2][2], s[qt][2 * ks2][3]);
;         pk.u[2] = pack2(s[qt][2 * ks2 + 1][0], s[qt][2 * ks2 + 1][1]);
;         pk.u[3] = pack2(s[qt][2 * ks2 + 1][2], s[qt][2 * ks2 + 1][3]);
;         pf[qt][ks2] = pk.v;
;       }
;     }
;     if (n + 1 < ntiles) { AD_LOAD_V(knext) }
.LBB0_327:
	s_barrier
	s_waitcnt vmcnt(7)
	ds_write_b128 v158, v[52:55]
	s_waitcnt vmcnt(5)
	ds_write_b128 v159, v[72:75]
	ds_write_b128 v166, v[56:59]
	s_waitcnt vmcnt(4)
	ds_write_b128 v158, v[60:63] offset:15360
	s_waitcnt vmcnt(3)
	ds_write_b128 v158, v[100:103] offset:20480
	s_waitcnt vmcnt(2)
	ds_write_b128 v159, v[104:107] offset:20480
	s_waitcnt vmcnt(1)
	ds_write_b128 v166, v[108:111] offset:20480
	s_waitcnt vmcnt(0)
	ds_write_b128 v167, v[112:115] offset:20480
	v_lshl_add_u64 v[54:55], s[94:95], 0, v[152:153]
	v_add_co_u32_e32 v56, vcc, s12, v54
	v_lshl_add_u64 v[52:53], s[94:95], 0, v[154:155]
	s_nop 0
	v_addc_co_u32_e32 v57, vcc, 0, v55, vcc
	v_add_co_u32_e32 v60, vcc, s12, v52
	s_waitcnt lgkmcnt(0)
	s_nop 0
	v_addc_co_u32_e32 v61, vcc, 0, v53, vcc
	s_barrier
	s_setprio 1
	ds_read_b128 v[186:189], v157
	ds_read_b128 v[190:193], v157 offset:64
	ds_read_b128 v[194:197], v157 offset:640
	ds_read_b128 v[198:201], v157 offset:704
	ds_read_b128 v[202:205], v157 offset:5120
	ds_read_b128 v[128:131], v157 offset:5184
	ds_read_b128 v[242:245], v157 offset:5760
	ds_read_b128 v[246:249], v157 offset:5824
	global_load_dwordx4 v[52:55], v[56:57], off
	global_load_dwordx4 v[56:59], v[56:57], off offset:128
	global_load_dwordx4 v[72:75], v[60:61], off
	global_load_dwordx4 v[60:63], v[60:61], off offset:128
	s_waitcnt lgkmcnt(7)
	v_mfma_f32_16x16x32_bf16 v[108:111], v[186:189], v[12:15], v[0:3]
	v_mfma_f32_16x16x32_bf16 v[100:103], v[186:189], v[16:19], v[0:3]
	s_waitcnt lgkmcnt(6)
	v_mfma_f32_16x16x32_bf16 v[108:111], v[190:193], v[4:7], v[108:111]
	v_mfma_f32_16x16x32_bf16 v[100:103], v[190:193], v[8:11], v[100:103]
	s_waitcnt lgkmcnt(5)
	v_mfma_f32_16x16x32_bf16 v[116:119], v[194:197], v[12:15], v[0:3]
	v_mfma_f32_16x16x32_bf16 v[104:107], v[194:197], v[16:19], v[0:3]
	s_waitcnt lgkmcnt(4)
	v_mfma_f32_16x16x32_bf16 v[116:119], v[198:201], v[4:7], v[116:119]
	v_mfma_f32_16x16x32_bf16 v[104:107], v[198:201], v[8:11], v[104:107]
	s_waitcnt lgkmcnt(3)
	v_mfma_f32_16x16x32_bf16 v[124:127], v[202:205], v[12:15], v[0:3]
	v_mfma_f32_16x16x32_bf16 v[112:115], v[202:205], v[16:19], v[0:3]
	s_waitcnt lgkmcnt(2)
	v_mfma_f32_16x16x32_bf16 v[124:127], v[128:131], v[4:7], v[124:127]
	v_mfma_f32_16x16x32_bf16 v[112:115], v[128:131], v[8:11], v[112:115]
	s_waitcnt lgkmcnt(1)
	v_mfma_f32_16x16x32_bf16 v[182:185], v[242:245], v[12:15], v[0:3]
	v_mfma_f32_16x16x32_bf16 v[120:123], v[242:245], v[16:19], v[0:3]
	s_waitcnt lgkmcnt(0)
	v_mfma_f32_16x16x32_bf16 v[182:185], v[246:249], v[4:7], v[182:185]
	v_mfma_f32_16x16x32_bf16 v[120:123], v[246:249], v[8:11], v[120:123]
	ds_read_b128 v[242:245], v156 offset:20480
	ds_read_b128 v[246:249], v156 offset:23040
	ds_read_b128 v[250:253], v156 offset:25600
	s_setprio 0
	v_exp_f32_e32 v129, v108
	v_exp_f32_e32 v128, v100
	v_exp_f32_e32 v109, v109
	v_exp_f32_e32 v108, v101
	v_exp_f32_e32 v131, v110
	v_exp_f32_e32 v130, v102
	v_exp_f32_e32 v111, v111
	v_exp_f32_e32 v110, v103
	v_exp_f32_e32 v187, v116
	v_exp_f32_e32 v186, v104
	v_pk_add_f32 v[100:101], v[128:129], 0 op_sel_hi:[1,0]
	v_exp_f32_e32 v189, v117
	v_exp_f32_e32 v188, v105
	v_pk_add_f32 v[100:101], v[108:109], v[100:101]
	v_exp_f32_e32 v191, v118
	v_pk_add_f32 v[100:101], v[130:131], v[100:101]
	v_exp_f32_e32 v190, v106
	v_exp_f32_e32 v193, v119
	v_pk_add_f32 v[100:101], v[110:111], v[100:101]
	v_exp_f32_e32 v192, v107
	v_exp_f32_e32 v195, v124
	v_pk_add_f32 v[100:101], v[100:101], v[186:187]
	v_exp_f32_e32 v194, v112
	v_exp_f32_e32 v197, v125
	v_pk_add_f32 v[100:101], v[188:189], v[100:101]
	v_exp_f32_e32 v196, v113
	v_exp_f32_e32 v199, v126
	v_exp_f32_e32 v198, v114
	v_pk_add_f32 v[100:101], v[190:191], v[100:101]
	v_exp_f32_e32 v201, v127
	v_exp_f32_e32 v200, v115
	v_pk_add_f32 v[100:101], v[192:193], v[100:101]
	v_exp_f32_e32 v203, v182
	v_exp_f32_e32 v202, v120
	v_pk_add_f32 v[100:101], v[100:101], v[194:195]
	v_exp_f32_e32 v183, v183
	v_exp_f32_e32 v182, v121
	v_pk_add_f32 v[100:101], v[196:197], v[100:101]
	v_exp_f32_e32 v205, v184
	v_exp_f32_e32 v204, v122
	v_pk_add_f32 v[100:101], v[198:199], v[100:101]
	v_exp_f32_e32 v185, v185
	v_exp_f32_e32 v184, v123
	v_pk_add_f32 v[100:101], v[200:201], v[100:101]
	v_cvt_pk_bf16_f32 v124, v129, v109
	v_pk_add_f32 v[100:101], v[100:101], v[202:203]
	v_cvt_pk_bf16_f32 v128, v128, v108
	v_pk_add_f32 v[100:101], v[182:183], v[100:101]
	v_lshl_add_u64 v[112:113], s[94:95], 0, v[150:151]
	v_pk_add_f32 v[100:101], v[204:205], v[100:101]
	v_lshl_add_u64 v[108:109], s[94:95], 0, v[138:139]
	v_pk_add_f32 v[100:101], v[184:185], v[100:101]
	v_lshl_add_u64 v[104:105], s[94:95], 0, v[136:137]
	v_pk_add_f32 v[132:133], v[132:133], v[100:101]
	v_lshl_add_u64 v[100:101], s[94:95], 0, v[134:135]
	v_cvt_pk_bf16_f32 v125, v131, v111
	v_cvt_pk_bf16_f32 v129, v130, v110
	global_load_dwordx4 v[100:103], v[100:101], off
	s_nop 0
	global_load_dwordx4 v[104:107], v[104:105], off
	s_nop 0
	global_load_dwordx4 v[108:111], v[108:109], off
	s_nop 0
	global_load_dwordx4 v[112:115], v[112:113], off
	v_cvt_pk_bf16_f32 v126, v187, v189
	v_cvt_pk_bf16_f32 v127, v191, v193
	v_cvt_pk_bf16_f32 v116, v195, v197
	v_cvt_pk_bf16_f32 v117, v199, v201
	v_cvt_pk_bf16_f32 v118, v203, v183
	v_cvt_pk_bf16_f32 v119, v205, v185
	v_cvt_pk_bf16_f32 v130, v186, v188
	v_cvt_pk_bf16_f32 v131, v190, v192
	v_cvt_pk_bf16_f32 v120, v194, v196
	v_cvt_pk_bf16_f32 v121, v198, v200
	v_cvt_pk_bf16_f32 v122, v202, v182
	v_cvt_pk_bf16_f32 v123, v204, v184
	s_setprio 1
	ds_read_b128 v[182:185], v156 offset:28160
	ds_read_b128 v[186:189], v156 offset:30720
	ds_read_b128 v[190:193], v156 offset:33280
	ds_read_b128 v[194:197], v156 offset:35840
	ds_read_b128 v[198:201], v156 offset:38400
	ds_read_b128 v[202:205], v156 offset:20544
	s_waitcnt lgkmcnt(8)
; __device__ __forceinline__ void attn_diff32(const bf16_t* __restrict__ Qp, const bf16_t* __restrict__ Kp,
;                                             const bf16_t* __restrict__ Vtp, int ntiles, float negM,
;                                             f32x4 (&o)[2][8], float (&l)[2], char* smem) {
;     ...
;     __syncthreads();
;     *(uint4*)(sK + (lr) * LSTR + lch) = rk00;
;     *(uint4*)(sK + (lr + 32) * LSTR + lch) = rk01;
;     *(uint4*)(sK + (64 + lr) * LSTR + lch) = rk10;
;     *(uint4*)(sK + (64 + lr + 32) * LSTR + lch) = rk11;
;     *(uint4*)(sVt + (lr) * LSTR + lch) = rv0;
;     *(uint4*)(sVt + (lr + 32) * LSTR + lch) = rv1;
;     *(uint4*)(sVt + (lr + 64) * LSTR + lch) = rv2;
;     *(uint4*)(sVt + (lr + 96) * LSTR + lch) = rv3;
;     __syncthreads();
;     const int knext = (n + 1) * 64;
;     if (n + 1 < ntiles) { AD_LOAD_K(knext) }
;     f32x4 s[2][4];
;     __builtin_amdgcn_s_setprio(1);
; #pragma unroll
;     for (int kt = 0; kt < 4; ++kt) {
;       s[0][kt] = (f32x4){negM, negM, negM, negM};
;       s[1][kt] = (f32x4){negM, negM, negM, negM};
;       const int krow = 32 * (kt >> 1) + (l15 >> 2) * 8 + (kt & 1) * 4 + (l15 & 3);
; #pragma unroll
;       for (int ks = 0; ks < 2; ++ks) {
;         const bf16x8 kf = *(const bf16x8*)(sKc + krow * LSTR + ks * 32 + quad * 8);
;         s[0][kt] = __builtin_amdgcn_mfma_f32_16x16x32_bf16(kf, qf[0][ks], s[0][kt], 0, 0, 0);
;         s[1][kt] = __builtin_amdgcn_mfma_f32_16x16x32_bf16(kf, qf[1][ks], s[1][kt], 0, 0, 0);
;       }
;     }
;     ...
;     __builtin_amdgcn_s_setprio(1);
; #pragma unroll
;     for (int ks2 = 0; ks2 < 2; ++ks2)
; #pragma unroll
;       for (int dt = 0; dt < 8; ++dt) {
;         const bf16x8 vf = *(const bf16x8*)(sVt + (dt * 16 + l15) * LSTR + 32 * ks2 + quad * 8);
;         o[0][dt] = __builtin_amdgcn_mfma_f32_16x16x32_bf16(vf, pf[0][ks2], o[0][dt], 0, 0, 0);
;         o[1][dt] = __builtin_amdgcn_mfma_f32_16x16x32_bf16(vf, pf[1][ks2], o[1][dt], 0, 0, 0);
;       }
;     __builtin_amdgcn_s_setprio(0);
	v_mfma_f32_16x16x32_bf16 v[40:43], v[242:245], v[124:127], v[40:43]
	v_mfma_f32_16x16x32_bf16 v[20:23], v[242:245], v[128:131], v[20:23]
	ds_read_b128 v[242:245], v156 offset:23104
	v_lshl_add_u64 v[134:135], v[134:135], 0, s[24:25]
	s_waitcnt lgkmcnt(8)
	v_mfma_f32_16x16x32_bf16 v[48:51], v[246:249], v[124:127], v[48:51]
	v_mfma_f32_16x16x32_bf16 v[24:27], v[246:249], v[128:131], v[24:27]
	ds_read_b128 v[246:249], v156 offset:25664
	v_lshl_add_u64 v[136:137], v[136:137], 0, s[24:25]
	s_waitcnt lgkmcnt(8)
	v_mfma_f32_16x16x32_bf16 v[68:71], v[250:253], v[124:127], v[68:71]
	v_mfma_f32_16x16x32_bf16 v[28:31], v[250:253], v[128:131], v[28:31]
	ds_read_b128 v[250:253], v156 offset:28224
	v_lshl_add_u64 v[138:139], v[138:139], 0, s[24:25]
	s_waitcnt lgkmcnt(8)
	v_mfma_f32_16x16x32_bf16 v[76:79], v[182:185], v[124:127], v[76:79]
	v_mfma_f32_16x16x32_bf16 v[32:35], v[182:185], v[128:131], v[32:35]
	ds_read_b128 v[182:185], v156 offset:30784
	v_lshl_add_u64 v[150:151], v[150:151], 0, s[24:25]
	s_waitcnt lgkmcnt(8)
	v_mfma_f32_16x16x32_bf16 v[80:83], v[186:189], v[124:127], v[80:83]
	v_mfma_f32_16x16x32_bf16 v[36:39], v[186:189], v[128:131], v[36:39]
	ds_read_b128 v[186:189], v156 offset:33344
	v_lshl_add_u64 v[152:153], v[152:153], 0, s[26:27]
	s_waitcnt lgkmcnt(8)
	v_mfma_f32_16x16x32_bf16 v[84:87], v[190:193], v[124:127], v[84:87]
	v_mfma_f32_16x16x32_bf16 v[44:47], v[190:193], v[128:131], v[44:47]
	ds_read_b128 v[190:193], v156 offset:35904
	v_lshl_add_u64 v[154:155], v[154:155], 0, s[26:27]
	s_waitcnt lgkmcnt(8)
	v_mfma_f32_16x16x32_bf16 v[88:91], v[194:197], v[124:127], v[88:91]
	v_mfma_f32_16x16x32_bf16 v[64:67], v[194:197], v[128:131], v[64:67]
	ds_read_b128 v[194:197], v156 offset:38464
	s_waitcnt lgkmcnt(8)
	v_mfma_f32_16x16x32_bf16 v[96:99], v[198:201], v[124:127], v[96:99]
	v_mfma_f32_16x16x32_bf16 v[92:95], v[198:201], v[128:131], v[92:95]
	s_waitcnt lgkmcnt(7)
	v_mfma_f32_16x16x32_bf16 v[40:43], v[202:205], v[116:119], v[40:43]
	v_mfma_f32_16x16x32_bf16 v[20:23], v[202:205], v[120:123], v[20:23]
	s_waitcnt lgkmcnt(6)
	v_mfma_f32_16x16x32_bf16 v[48:51], v[242:245], v[116:119], v[48:51]
	v_mfma_f32_16x16x32_bf16 v[24:27], v[242:245], v[120:123], v[24:27]
	s_waitcnt lgkmcnt(5)
	v_mfma_f32_16x16x32_bf16 v[68:71], v[246:249], v[116:119], v[68:71]
	v_mfma_f32_16x16x32_bf16 v[28:31], v[246:249], v[120:123], v[28:31]
	s_waitcnt lgkmcnt(4)
	v_mfma_f32_16x16x32_bf16 v[76:79], v[250:253], v[116:119], v[76:79]
	v_mfma_f32_16x16x32_bf16 v[32:35], v[250:253], v[120:123], v[32:35]
	s_waitcnt lgkmcnt(3)
	v_mfma_f32_16x16x32_bf16 v[80:83], v[182:185], v[116:119], v[80:83]
	v_mfma_f32_16x16x32_bf16 v[36:39], v[182:185], v[120:123], v[36:39]
	s_waitcnt lgkmcnt(2)
	v_mfma_f32_16x16x32_bf16 v[84:87], v[186:189], v[116:119], v[84:87]
	v_mfma_f32_16x16x32_bf16 v[44:47], v[186:189], v[120:123], v[44:47]
	s_waitcnt lgkmcnt(1)
	v_mfma_f32_16x16x32_bf16 v[88:91], v[190:193], v[116:119], v[88:91]
	v_mfma_f32_16x16x32_bf16 v[64:67], v[190:193], v[120:123], v[64:67]
	s_waitcnt lgkmcnt(0)
	v_mfma_f32_16x16x32_bf16 v[96:99], v[194:197], v[116:119], v[96:99]
	v_mfma_f32_16x16x32_bf16 v[92:95], v[194:197], v[120:123], v[92:95]
	s_setprio 0
	s_add_i32 s0, s0, -1
	s_cmp_lg_u32 s0, 0
	s_cbranch_scc1 .LBB0_327
	s_barrier
	s_waitcnt vmcnt(7)
	ds_write_b128 v158, v[52:55]
	s_waitcnt vmcnt(5)
	ds_write_b128 v159, v[72:75]
	ds_write_b128 v166, v[56:59]
	s_waitcnt vmcnt(4)
	ds_write_b128 v158, v[60:63] offset:15360
	s_waitcnt vmcnt(3)
	ds_write_b128 v158, v[100:103] offset:20480
	s_waitcnt vmcnt(2)
	ds_write_b128 v159, v[104:107] offset:20480
	s_waitcnt vmcnt(1)
	ds_write_b128 v166, v[108:111] offset:20480
	s_waitcnt vmcnt(0)
	ds_write_b128 v167, v[112:115] offset:20480
	s_waitcnt lgkmcnt(0)
	s_barrier
	s_setprio 1
	ds_read_b128 v[52:55], v157
	ds_read_b128 v[60:63], v157 offset:64
	s_waitcnt lgkmcnt(1)
	v_mfma_f32_16x16x32_bf16 v[56:59], v[52:55], v[12:15], v[0:3]
	ds_read_b128 v[100:103], v157 offset:704
	ds_read_b128 v[108:111], v157 offset:5184
	v_mfma_f32_16x16x32_bf16 v[52:55], v[52:55], v[16:19], v[0:3]
	s_waitcnt lgkmcnt(2)
	v_mfma_f32_16x16x32_bf16 v[56:59], v[60:63], v[4:7], v[56:59]
	v_mfma_f32_16x16x32_bf16 v[52:55], v[60:63], v[8:11], v[52:55]
	ds_read_b128 v[60:63], v157 offset:640
	s_waitcnt lgkmcnt(0)
	v_mfma_f32_16x16x32_bf16 v[72:75], v[60:63], v[12:15], v[0:3]
	v_mfma_f32_16x16x32_bf16 v[60:63], v[60:63], v[16:19], v[0:3]
	v_mfma_f32_16x16x32_bf16 v[72:75], v[100:103], v[4:7], v[72:75]
	v_mfma_f32_16x16x32_bf16 v[60:63], v[100:103], v[8:11], v[60:63]
	ds_read_b128 v[100:103], v157 offset:5120
	s_waitcnt lgkmcnt(0)
	v_mfma_f32_16x16x32_bf16 v[104:107], v[100:103], v[12:15], v[0:3]
	v_mfma_f32_16x16x32_bf16 v[100:103], v[100:103], v[16:19], v[0:3]
	v_mfma_f32_16x16x32_bf16 v[104:107], v[108:111], v[4:7], v[104:107]
	v_mfma_f32_16x16x32_bf16 v[100:103], v[108:111], v[8:11], v[100:103]
	ds_read_b128 v[108:111], v157 offset:5760
	s_waitcnt lgkmcnt(0)
	v_mfma_f32_16x16x32_bf16 v[12:15], v[108:111], v[12:15], v[0:3]
	v_mfma_f32_16x16x32_bf16 v[16:19], v[108:111], v[16:19], v[0:3]
	ds_read_b128 v[108:111], v157 offset:5824
	s_waitcnt lgkmcnt(0)
; __device__ __forceinline__ float fexp2(float x) { return __builtin_amdgcn_exp2f(x); }
; __device__ __forceinline__ void attn_diff32(const bf16_t* __restrict__ Qp, const bf16_t* __restrict__ Kp,
;                                             const bf16_t* __restrict__ Vtp, int ntiles, float negM,
;                                             f32x4 (&o)[2][8], float (&l)[2], char* smem) {
;     ...
; #pragma unroll
;     for (int qt = 0; qt < 2; ++qt) {
;       float ls = 0.f;
; #pragma unroll
;       for (int kt = 0; kt < 4; ++kt)
; #pragma unroll
;         for (int e = 0; e < 4; ++e) {
;           s[qt][kt][e] = fexp2(s[qt][kt][e]);
;           ls += s[qt][kt][e];
;         }
;       l[qt] += ls;
; #pragma unroll
;       for (int ks2 = 0; ks2 < 2; ++ks2) {
;         union { uint32_t u[4]; bf16x8 v; } pk;
;         pk.u[0] = pack2(s[qt][2 * ks2][0], s[qt][2 * ks2][1]);
;         pk.u[1] = pack2(s[qt][2 * ks2][2], s[qt][2 * ks2][3]);
;         pk.u[2] = pack2(s[qt][2 * ks2 + 1][0], s[qt][2 * ks2 + 1][1]);
;         pk.u[3] = pack2(s[qt][2 * ks2 + 1][2], s[qt][2 * ks2 + 1][3]);
;         pf[qt][ks2] = pk.v;
;       }
;     }
;     if (n + 1 < ntiles) { AD_LOAD_V(knext) }
;     __builtin_amdgcn_s_setprio(1);
; #pragma unroll
;     for (int ks2 = 0; ks2 < 2; ++ks2)
; #pragma unroll
;       for (int dt = 0; dt < 8; ++dt) {
;         const bf16x8 vf = *(const bf16x8*)(sVt + (dt * 16 + l15) * LSTR + 32 * ks2 + quad * 8);
;         o[0][dt] = __builtin_amdgcn_mfma_f32_16x16x32_bf16(vf, pf[0][ks2], o[0][dt], 0, 0, 0);
;         o[1][dt] = __builtin_amdgcn_mfma_f32_16x16x32_bf16(vf, pf[1][ks2], o[1][dt], 0, 0, 0);
;       }
;     __builtin_amdgcn_s_setprio(0);
	v_mfma_f32_16x16x32_bf16 v[4:7], v[108:111], v[4:7], v[12:15]
	v_mfma_f32_16x16x32_bf16 v[8:11], v[108:111], v[8:11], v[16:19]
	s_setprio 0
	s_nop 1
	v_exp_f32_e32 v12, v56
	v_exp_f32_e32 v13, v57
	v_exp_f32_e32 v14, v58
	v_exp_f32_e32 v15, v59
	v_add_f32_e32 v16, 0, v12
	v_exp_f32_e32 v17, v72
	v_add_f32_e32 v16, v13, v16
	v_exp_f32_e32 v18, v73
	v_add_f32_e32 v16, v14, v16
	v_exp_f32_e32 v19, v74
	v_add_f32_e32 v16, v15, v16
	v_exp_f32_e32 v56, v75
	v_add_f32_e32 v16, v16, v17
	v_exp_f32_e32 v57, v104
	v_add_f32_e32 v16, v18, v16
	v_exp_f32_e32 v58, v105
	v_add_f32_e32 v16, v19, v16
	v_exp_f32_e32 v59, v106
	v_add_f32_e32 v16, v56, v16
	v_exp_f32_e32 v72, v107
	v_add_f32_e32 v16, v16, v57
	v_exp_f32_e32 v73, v4
	v_add_f32_e32 v16, v58, v16
	v_exp_f32_e32 v74, v5
	v_add_f32_e32 v16, v59, v16
	v_exp_f32_e32 v75, v6
	v_add_f32_e32 v16, v72, v16
	v_exp_f32_e32 v104, v7
	v_add_f32_e32 v4, v16, v73
	v_exp_f32_e32 v16, v52
	v_add_f32_e32 v4, v74, v4
	v_exp_f32_e32 v52, v53
	v_add_f32_e32 v4, v75, v4
	v_exp_f32_e32 v53, v54
	v_add_f32_e32 v4, v104, v4
	v_exp_f32_e32 v54, v55
	v_add_f32_e32 v108, v133, v4
	v_add_f32_e32 v4, 0, v16
	v_exp_f32_e32 v55, v60
	v_add_f32_e32 v4, v52, v4
	v_exp_f32_e32 v60, v61
	v_add_f32_e32 v4, v53, v4
	v_exp_f32_e32 v61, v62
	v_add_f32_e32 v4, v54, v4
	v_exp_f32_e32 v62, v63
	v_add_f32_e32 v4, v4, v55
	v_exp_f32_e32 v5, v100
	v_add_f32_e32 v4, v60, v4
	v_exp_f32_e32 v6, v101
	v_add_f32_e32 v4, v61, v4
	v_exp_f32_e32 v7, v102
	v_add_f32_e32 v4, v62, v4
	v_exp_f32_e32 v63, v103
	v_add_f32_e32 v4, v4, v5
	v_exp_f32_e32 v8, v8
	v_add_f32_e32 v4, v6, v4
	v_exp_f32_e32 v9, v9
	v_add_f32_e32 v4, v7, v4
	v_exp_f32_e32 v10, v10
	v_add_f32_e32 v4, v63, v4
	v_exp_f32_e32 v11, v11
	v_add_f32_e32 v4, v4, v8
	v_add_f32_e32 v4, v9, v4
	v_add_f32_e32 v4, v10, v4
	v_add_f32_e32 v4, v11, v4
	v_add_f32_e32 v109, v132, v4
	v_cvt_pk_bf16_f32 v4, v5, v6
	v_cvt_pk_bf16_f32 v5, v7, v63
	v_cvt_pk_bf16_f32 v6, v8, v9
	v_cvt_pk_bf16_f32 v7, v10, v11
	v_cvt_pk_bf16_f32 v8, v16, v52
	v_cvt_pk_bf16_f32 v9, v53, v54
	v_cvt_pk_bf16_f32 v10, v55, v60
	v_cvt_pk_bf16_f32 v11, v61, v62
	v_cvt_pk_bf16_f32 v60, v57, v58
	v_cvt_pk_bf16_f32 v61, v59, v72
	v_cvt_pk_bf16_f32 v62, v73, v74
	v_cvt_pk_bf16_f32 v63, v75, v104
	v_cvt_pk_bf16_f32 v12, v12, v13
	v_cvt_pk_bf16_f32 v13, v14, v15
	v_cvt_pk_bf16_f32 v14, v17, v18
	v_cvt_pk_bf16_f32 v15, v19, v56
	s_setprio 1
	ds_read_b128 v[16:19], v156 offset:20480
	s_waitcnt lgkmcnt(0)
	v_mfma_f32_16x16x32_bf16 v[40:43], v[16:19], v[12:15], v[40:43]
	v_mfma_f32_16x16x32_bf16 v[16:19], v[16:19], v[8:11], v[20:23]
	s_nop 2
	ds_read_b128 v[20:23], v156 offset:23040
	s_waitcnt lgkmcnt(0)
	v_mfma_f32_16x16x32_bf16 v[48:51], v[20:23], v[12:15], v[48:51]
	v_mfma_f32_16x16x32_bf16 v[20:23], v[20:23], v[8:11], v[24:27]
	s_nop 2
	ds_read_b128 v[24:27], v156 offset:25600
	s_waitcnt lgkmcnt(0)
	v_mfma_f32_16x16x32_bf16 v[52:55], v[24:27], v[12:15], v[68:71]
	v_mfma_f32_16x16x32_bf16 v[24:27], v[24:27], v[8:11], v[28:31]
	s_nop 2
	ds_read_b128 v[28:31], v156 offset:28160
	s_waitcnt lgkmcnt(0)
	v_mfma_f32_16x16x32_bf16 v[68:71], v[28:31], v[12:15], v[76:79]
	v_mfma_f32_16x16x32_bf16 v[72:75], v[28:31], v[8:11], v[32:35]
	ds_read_b128 v[28:31], v156 offset:30720
	s_waitcnt lgkmcnt(0)
	v_mfma_f32_16x16x32_bf16 v[76:79], v[28:31], v[12:15], v[80:83]
	v_mfma_f32_16x16x32_bf16 v[80:83], v[28:31], v[8:11], v[36:39]
	ds_read_b128 v[28:31], v156 offset:33280
	s_waitcnt lgkmcnt(0)
	v_mfma_f32_16x16x32_bf16 v[84:87], v[28:31], v[12:15], v[84:87]
	v_mfma_f32_16x16x32_bf16 v[100:103], v[28:31], v[8:11], v[44:47]
	ds_read_b128 v[28:31], v156 offset:35840
	s_waitcnt lgkmcnt(0)
	v_mfma_f32_16x16x32_bf16 v[88:91], v[28:31], v[12:15], v[88:91]
	v_mfma_f32_16x16x32_bf16 v[104:107], v[28:31], v[8:11], v[64:67]
	ds_read_b128 v[28:31], v156 offset:38400
	s_waitcnt lgkmcnt(0)
	v_mfma_f32_16x16x32_bf16 v[92:95], v[28:31], v[8:11], v[92:95]
	ds_read_b128 v[8:11], v156 offset:20544
	s_waitcnt lgkmcnt(0)
	v_mfma_f32_16x16x32_bf16 v[64:67], v[8:11], v[60:63], v[40:43]
	v_mfma_f32_16x16x32_bf16 v[32:35], v[8:11], v[4:7], v[16:19]
	ds_read_b128 v[8:11], v156 offset:23104
	v_mfma_f32_16x16x32_bf16 v[96:99], v[28:31], v[12:15], v[96:99]
	s_waitcnt lgkmcnt(0)
	v_mfma_f32_16x16x32_bf16 v[56:59], v[8:11], v[60:63], v[48:51]
	v_mfma_f32_16x16x32_bf16 v[28:31], v[8:11], v[4:7], v[20:23]
	ds_read_b128 v[8:11], v156 offset:25664
	s_waitcnt lgkmcnt(0)
	v_mfma_f32_16x16x32_bf16 v[52:55], v[8:11], v[60:63], v[52:55]
	v_mfma_f32_16x16x32_bf16 v[24:27], v[8:11], v[4:7], v[24:27]
	ds_read_b128 v[8:11], v156 offset:28224
	s_waitcnt lgkmcnt(0)
	v_mfma_f32_16x16x32_bf16 v[36:39], v[8:11], v[60:63], v[68:71]
	s_nop 2
	ds_read_b128 v[68:71], v156 offset:38464
	v_mfma_f32_16x16x32_bf16 v[20:23], v[8:11], v[4:7], v[72:75]
	ds_read_b128 v[8:11], v156 offset:30784
	s_waitcnt lgkmcnt(0)
	v_mfma_f32_16x16x32_bf16 v[40:43], v[8:11], v[60:63], v[76:79]
	v_mfma_f32_16x16x32_bf16 v[16:19], v[8:11], v[4:7], v[80:83]
	ds_read_b128 v[8:11], v156 offset:33344
	s_waitcnt lgkmcnt(0)
	v_mfma_f32_16x16x32_bf16 v[44:47], v[8:11], v[60:63], v[84:87]
	v_mfma_f32_16x16x32_bf16 v[12:15], v[8:11], v[4:7], v[100:103]
	ds_read_b128 v[8:11], v156 offset:35904
	s_waitcnt lgkmcnt(0)
	v_mfma_f32_16x16x32_bf16 v[48:51], v[8:11], v[60:63], v[88:91]
	v_mfma_f32_16x16x32_bf16 v[8:11], v[8:11], v[4:7], v[104:107]
	v_mfma_f32_16x16x32_bf16 v[60:63], v[68:71], v[60:63], v[96:99]
	v_mfma_f32_16x16x32_bf16 v[4:7], v[68:71], v[4:7], v[92:95]
	s_setprio 0
	v_cmp_lt_i32_e32 vcc, v173, v174
	s_barrier
; __device__ __forceinline__ void attn_diff32(const bf16_t* __restrict__ Qp, const bf16_t* __restrict__ Kp,
;                                             const bf16_t* __restrict__ Vtp, int ntiles, float negM,
;                                             f32x4 (&o)[2][8], float (&l)[2], char* smem) {
;     ...
; #pragma unroll
;   for (int qt = 0; qt < 2; ++qt) {
;     l[qt] += __shfl_xor(l[qt], 16);
;     l[qt] += __shfl_xor(l[qt], 32);
;   }
; }
; __device__ __forceinline__ void phase_attn0(const Params& P, char* smem) {
;   char* ws = P.ws;
;   const bf16_t* AQ = (const bf16_t*)(ws + OFF_AQ);
;   const bf16_t* AK = (const bf16_t*)(ws + OFF_AK);
;   const bf16_t* AVT = (const bf16_t*)(ws + OFF_AVT);
;   const bf16_t* BQ = (const bf16_t*)(ws + OFF_BQ);
;   const bf16_t* BK = (const bf16_t*)(ws + OFF_BK);
;   const bf16_t* BVT = (const bf16_t*)(ws + OFF_BVT);
;   bf16_t* Acat = (bf16_t*)(ws + OFF_A);
;   const float lam = ((const float*)(ws + OFF_LAM))[0];
;   const float negM = -((const float*)(ws + OFF_LAM))[1];
;   const bool fixed_ok = ((const float*)(ws + OFF_LAM))[1] < 60.0f;
;   const float lambda_init = 0.2f;
;   const int lane = threadIdx.x & 63, wave = threadIdx.x >> 6, l15 = lane & 15, quad = lane >> 4;
;   for (int u = blockIdx.x; u < 2080; u += gridDim.x) {
;     int b, head, qb;
;     if (u < 2048) {
;       const int bh = u & 7;
;       b = bh >> 2; head = bh & 3; qb = 4 + (u >> 3);
;     }
;     else { const int cu = u - 2048; b = cu >> 4; head = (cu >> 2) & 3; qb = cu & 3; }
;     const int qk0 = qb * 64;
;     const int nseg = qb >= 4 ? 256 : 0;
;     f32x4 o[2][8];
;     float m[2], l[2];
;     if (fixed_ok) {
;       f32x4 o2[2][8];
;       float l2[2];
;       attn_diff32(AQ + (size_t)(b * TPB + qk0) * 512 + head * 128, AK + (size_t)(b * TPB) * 512 + head * 128,
;                   AVT + (size_t)(b * 4 + head) * 128 * TPB, 4 + nseg, negM, o2, l2, smem);
;       float* xch = (float*)smem;
;       const int cmap = wave >> 1, qg = wave & 1;
;       __syncthreads();
;       if (cmap == 1) {
; #pragma unroll
;         for (int qt = 0; qt < 2; ++qt) {
;           const float i1 = lam / l2[qt];
; #pragma unroll
;           for (int dt = 0; dt < 8; ++dt)
;             *(f32x4*)(xch + (size_t)((qg * 32 + qt * 16 + l15) * 128 + dt * 16 + quad * 4)) = o2[qt][dt] * i1;
;         }
;       }
	s_nop 0
	v_cndmask_b32_e32 v68, v172, v173, vcc
	v_cmp_lt_i32_e32 vcc, v175, v174
	v_lshlrev_b32_e32 v84, 2, v68
	s_nop 0
	v_cndmask_b32_e32 v68, v172, v175, vcc
	v_lshlrev_b32_e32 v85, 2, v68
	ds_bpermute_b32 v68, v84, v108
	s_waitcnt lgkmcnt(0)
	v_add_f32_e32 v68, v108, v68
	ds_bpermute_b32 v69, v85, v68
	s_waitcnt lgkmcnt(0)
	v_add_f32_e32 v74, v68, v69
	ds_bpermute_b32 v68, v84, v109
	s_waitcnt lgkmcnt(0)
	v_add_f32_e32 v68, v109, v68
	ds_bpermute_b32 v69, v85, v68
	s_waitcnt lgkmcnt(0)
	v_add_f32_e32 v86, v68, v69
	s_and_saveexec_b64 s[18:19], s[6:7]
	s_cbranch_execz .LBB0_330
	v_div_scale_f32 v68, s[2:3], v74, v74, v142
	v_rcp_f32_e32 v69, v68
	s_nop 0
	v_fma_f32 v70, -v68, v69, 1.0
	v_fmac_f32_e32 v69, v70, v69
	v_div_scale_f32 v70, vcc, v142, v74, v142
	v_mul_f32_e32 v71, v70, v69
	v_fma_f32 v72, -v68, v71, v70
	v_fmac_f32_e32 v71, v72, v69
	v_fma_f32 v68, -v68, v71, v70
	v_div_fmas_f32 v68, v68, v69, v71
	v_div_fixup_f32 v72, v68, v74, v142
	v_pk_mul_f32 v[70:71], v[66:67], v[72:73] op_sel_hi:[1,0]
	v_pk_mul_f32 v[68:69], v[64:65], v[72:73] op_sel_hi:[1,0]
	ds_write_b128 v169, v[68:71]
	v_pk_mul_f32 v[70:71], v[58:59], v[72:73] op_sel_hi:[1,0]
	v_pk_mul_f32 v[68:69], v[56:57], v[72:73] op_sel_hi:[1,0]
	ds_write_b128 v169, v[68:71] offset:64
	v_pk_mul_f32 v[70:71], v[54:55], v[72:73] op_sel_hi:[1,0]
	v_pk_mul_f32 v[68:69], v[52:53], v[72:73] op_sel_hi:[1,0]
	ds_write_b128 v169, v[68:71] offset:128
	v_pk_mul_f32 v[70:71], v[38:39], v[72:73] op_sel_hi:[1,0]
	v_pk_mul_f32 v[68:69], v[36:37], v[72:73] op_sel_hi:[1,0]
	ds_write_b128 v169, v[68:71] offset:192
	v_pk_mul_f32 v[70:71], v[42:43], v[72:73] op_sel_hi:[1,0]
	v_pk_mul_f32 v[68:69], v[40:41], v[72:73] op_sel_hi:[1,0]
	ds_write_b128 v169, v[68:71] offset:256
	v_pk_mul_f32 v[70:71], v[46:47], v[72:73] op_sel_hi:[1,0]
	v_pk_mul_f32 v[68:69], v[44:45], v[72:73] op_sel_hi:[1,0]
	ds_write_b128 v169, v[68:71] offset:320
	v_pk_mul_f32 v[70:71], v[50:51], v[72:73] op_sel_hi:[1,0]
	v_pk_mul_f32 v[68:69], v[48:49], v[72:73] op_sel_hi:[1,0]
	ds_write_b128 v169, v[68:71] offset:384
	v_pk_mul_f32 v[70:71], v[62:63], v[72:73] op_sel_hi:[1,0]
	v_pk_mul_f32 v[68:69], v[60:61], v[72:73] op_sel_hi:[1,0]
	ds_write_b128 v169, v[68:71] offset:448
	v_div_scale_f32 v68, s[2:3], v86, v86, v142
	v_rcp_f32_e32 v69, v68
	s_nop 0
	v_fma_f32 v70, -v68, v69, 1.0
	v_fmac_f32_e32 v69, v70, v69
	v_div_scale_f32 v70, vcc, v142, v86, v142
	v_mul_f32_e32 v71, v70, v69
	v_fma_f32 v72, -v68, v71, v70
	v_fmac_f32_e32 v71, v72, v69
	v_fma_f32 v68, -v68, v71, v70
	v_div_fmas_f32 v68, v68, v69, v71
	v_div_fixup_f32 v72, v68, v86, v142
	v_pk_mul_f32 v[70:71], v[34:35], v[72:73] op_sel_hi:[1,0]
	v_pk_mul_f32 v[68:69], v[32:33], v[72:73] op_sel_hi:[1,0]
	ds_write_b128 v169, v[68:71] offset:8192
	v_pk_mul_f32 v[70:71], v[30:31], v[72:73] op_sel_hi:[1,0]
	v_pk_mul_f32 v[68:69], v[28:29], v[72:73] op_sel_hi:[1,0]
	ds_write_b128 v169, v[68:71] offset:8256
	v_pk_mul_f32 v[70:71], v[26:27], v[72:73] op_sel_hi:[1,0]
	v_pk_mul_f32 v[68:69], v[24:25], v[72:73] op_sel_hi:[1,0]
	ds_write_b128 v169, v[68:71] offset:8320
	v_pk_mul_f32 v[70:71], v[22:23], v[72:73] op_sel_hi:[1,0]
	v_pk_mul_f32 v[68:69], v[20:21], v[72:73] op_sel_hi:[1,0]
	ds_write_b128 v169, v[68:71] offset:8384
	v_pk_mul_f32 v[70:71], v[18:19], v[72:73] op_sel_hi:[1,0]
	v_pk_mul_f32 v[68:69], v[16:17], v[72:73] op_sel_hi:[1,0]
	ds_write_b128 v169, v[68:71] offset:8448
	v_pk_mul_f32 v[70:71], v[14:15], v[72:73] op_sel_hi:[1,0]
	v_pk_mul_f32 v[68:69], v[12:13], v[72:73] op_sel_hi:[1,0]
	ds_write_b128 v169, v[68:71] offset:8512
	v_pk_mul_f32 v[70:71], v[10:11], v[72:73] op_sel_hi:[1,0]
	v_pk_mul_f32 v[68:69], v[8:9], v[72:73] op_sel_hi:[1,0]
	ds_write_b128 v169, v[68:71] offset:8576
	v_pk_mul_f32 v[70:71], v[6:7], v[72:73] op_sel_hi:[1,0]
	v_pk_mul_f32 v[68:69], v[4:5], v[72:73] op_sel_hi:[1,0]
	ds_write_b128 v169, v[68:71] offset:8640
